# conv boundary fixup loop: rounds 0 and 1 load together into two register sets (one memory round trip fewer per layer), third partial round under its lane mask
# baseline (speedup 1.0000x reference)
; __device__ __forceinline__ void fixup_panel(int wave_s, int pm, const float* hbuf, const float* cw, const float* cb, bf16* act) {
;     ...
;     for (int cgi = tid; cgi < DFF / 4; cgi += NTHR) { const int ch = cgi * 4;
;         const int colg = 256 * (ch >> 7) + (ch & 127);
;         const float* hp = hbuf + ((size_t)(pm - 1) * 4 + 2) * NUP + colg; const float* hc = hbuf + (size_t)pm * 4 * NUP + colg;
;         const f32x4 gm2 = *(const f32x4*)hp, gm1 = *(const f32x4*)(hp + NUP), g0 = *(const f32x4*)hc, g1 = *(const f32x4*)(hc + NUP);
;         const f32x4 vm2 = *(const f32x4*)(hp + 128), vm1 = *(const f32x4*)(hp + NUP + 128), v0 = *(const f32x4*)(hc + 128), v1 = *(const f32x4*)(hc + NUP + 128);
;         const f32x4 wg0 = *(const f32x4*)(cw + ch), wg1 = *(const f32x4*)(cw + NUP + ch), wg2 = *(const f32x4*)(cw + 2 * NUP + ch), bg = *(const f32x4*)(cb + ch);
;         const f32x4 wv0 = *(const f32x4*)(cw + DFF + ch), wv1 = *(const f32x4*)(cw + NUP + DFF + ch), wv2 = *(const f32x4*)(cw + 2 * NUP + DFF + ch), bv = *(const f32x4*)(cb + DFF + ch);
;         const f32x4 gc0 = wg0 * gm2 + wg1 * gm1 + wg2 * g0 + bg, vc0 = wv0 * vm2 + wv1 * vm1 + wv2 * v0 + bv;
;         const f32x4 gc1 = wg0 * gm1 + wg1 * g0 + wg2 * g1 + bg, vc1 = wv0 * vm1 + wv1 * v0 + wv2 * v1 + bv;
.LBB0_765:
	v_and_b32_e32 v3, 0x7c, v2
	s_movk_i32 s2, 0xff00
	v_and_or_b32 v6, v4, s2, v3
	v_ashrrev_i32_e32 v7, 31, v6
	v_lshlrev_b64 v[6:7], 2, v[6:7]
	v_lshl_add_u64 v[22:23], s[20:21], 0, v[6:7]
	v_add_co_u32_e32 v26, vcc, 0xb000, v22
	v_lshl_add_u64 v[30:31], s[26:27], 0, v[6:7]
	s_nop 0
	v_addc_co_u32_e32 v27, vcc, 0, v23, vcc
	v_ashrrev_i32_e32 v3, 31, v2
	v_add_co_u32_e32 v34, vcc, 0xb000, v30
	v_lshlrev_b64 v[66:67], 2, v[2:3]
	s_nop 0
	v_addc_co_u32_e32 v35, vcc, 0, v31, vcc
	v_lshl_add_u64 v[38:39], s[12:13], 0, v[66:67]
	v_lshl_add_u64 v[42:43], s[28:29], 0, v[66:67]
	global_load_dwordx4 v[6:9], v[22:23], off
	global_load_dwordx4 v[10:13], v[26:27], off
	global_load_dwordx4 v[14:17], v[30:31], off
	global_load_dwordx4 v[18:21], v[34:35], off
	s_nop 0
	global_load_dwordx4 v[22:25], v[22:23], off offset:512
	s_nop 0
	global_load_dwordx4 v[26:29], v[26:27], off offset:512
	s_nop 0
	global_load_dwordx4 v[30:33], v[30:31], off offset:512
	s_nop 0
	global_load_dwordx4 v[34:37], v[34:35], off offset:512
	v_lshl_add_u64 v[46:47], s[30:31], 0, v[66:67]
	global_load_dwordx4 v[38:41], v[38:39], off
	v_lshl_add_u64 v[50:51], s[10:11], 0, v[66:67]
	global_load_dwordx4 v[42:45], v[42:43], off
	v_lshl_add_u64 v[54:55], s[88:89], 0, v[66:67]
	global_load_dwordx4 v[46:49], v[46:47], off
	v_lshl_add_u64 v[58:59], s[90:91], 0, v[66:67]
	global_load_dwordx4 v[50:53], v[50:51], off
	v_lshl_add_u64 v[62:63], s[92:93], 0, v[66:67]
	global_load_dwordx4 v[54:57], v[54:55], off
	v_lshl_add_u64 v[66:67], s[96:97], 0, v[66:67]
	global_load_dwordx4 v[58:61], v[58:59], off
	global_load_dwordx4 v[62:65], v[62:63], off
	global_load_dwordx4 v[66:69], v[66:67], off
	v_add_u32_e32 v126, 0x800, v2
	v_add_u32_e32 v128, 0x1000, v4
	v_and_b32_e32 v127, 0x7c, v126
	s_movk_i32 s2, 0xff00
	v_and_or_b32 v130, v128, s2, v127
	v_ashrrev_i32_e32 v131, 31, v130
	v_lshlrev_b64 v[130:131], 2, v[130:131]
	v_lshl_add_u64 v[146:147], s[20:21], 0, v[130:131]
	v_add_co_u32_e32 v150, vcc, 0xb000, v146
	v_lshl_add_u64 v[154:155], s[26:27], 0, v[130:131]
	s_nop 0
	v_addc_co_u32_e32 v151, vcc, 0, v147, vcc
	v_ashrrev_i32_e32 v127, 31, v126
	v_add_co_u32_e32 v158, vcc, 0xb000, v154
	v_lshlrev_b64 v[190:191], 2, v[126:127]
	s_nop 0
	v_addc_co_u32_e32 v159, vcc, 0, v155, vcc
	v_lshl_add_u64 v[162:163], s[12:13], 0, v[190:191]
	v_lshl_add_u64 v[166:167], s[28:29], 0, v[190:191]
	global_load_dwordx4 v[130:133], v[146:147], off
	global_load_dwordx4 v[134:137], v[150:151], off
	global_load_dwordx4 v[138:141], v[154:155], off
	global_load_dwordx4 v[142:145], v[158:159], off
	s_nop 0
	global_load_dwordx4 v[146:149], v[146:147], off offset:512
	s_nop 0
	global_load_dwordx4 v[150:153], v[150:151], off offset:512
	s_nop 0
	global_load_dwordx4 v[154:157], v[154:155], off offset:512
	s_nop 0
	global_load_dwordx4 v[158:161], v[158:159], off offset:512
	v_lshl_add_u64 v[170:171], s[30:31], 0, v[190:191]
	global_load_dwordx4 v[162:165], v[162:163], off
	v_lshl_add_u64 v[174:175], s[10:11], 0, v[190:191]
	global_load_dwordx4 v[166:169], v[166:167], off
	v_lshl_add_u64 v[178:179], s[88:89], 0, v[190:191]
	global_load_dwordx4 v[170:173], v[170:171], off
	v_lshl_add_u64 v[182:183], s[90:91], 0, v[190:191]
	global_load_dwordx4 v[174:177], v[174:175], off
	v_lshl_add_u64 v[186:187], s[92:93], 0, v[190:191]
	global_load_dwordx4 v[178:181], v[178:179], off
	v_lshl_add_u64 v[190:191], s[96:97], 0, v[190:191]
	global_load_dwordx4 v[182:185], v[182:183], off
	global_load_dwordx4 v[186:189], v[186:187], off
	global_load_dwordx4 v[190:193], v[190:191], off
	s_waitcnt vmcnt(22)
	v_pk_mul_f32 v[72:73], v[10:11], v[42:43]
	s_nop 0
	v_pk_fma_f32 v[6:7], v[6:7], v[38:39], v[72:73]
	v_pk_mul_f32 v[42:43], v[14:15], v[42:43]
	s_waitcnt vmcnt(21)
	v_pk_fma_f32 v[6:7], v[14:15], v[46:47], v[6:7]
	v_pk_fma_f32 v[10:11], v[10:11], v[38:39], v[42:43]
	s_waitcnt vmcnt(20)
	v_pk_add_f32 v[6:7], v[50:51], v[6:7]
	v_pk_fma_f32 v[10:11], v[18:19], v[46:47], v[10:11]
	v_mul_f32_e32 v5, 0xbfb8aa3b, v6
	v_exp_f32_e32 v5, v5
	v_pk_add_f32 v[10:11], v[50:51], v[10:11]
	v_pk_mul_f32 v[70:71], v[12:13], v[44:45]
	s_waitcnt vmcnt(18)
	v_pk_mul_f32 v[76:77], v[26:27], v[58:59]
	v_add_f32_e32 v5, 1.0, v5
	v_rcp_f32_e32 v14, v5
	v_mul_f32_e32 v5, 0xbfb8aa3b, v7
	v_exp_f32_e32 v5, v5
	v_pk_fma_f32 v[8:9], v[8:9], v[40:41], v[70:71]
	v_pk_mul_f32 v[44:45], v[16:17], v[44:45]
	v_pk_fma_f32 v[8:9], v[16:17], v[48:49], v[8:9]
	v_add_f32_e32 v5, 1.0, v5
	v_rcp_f32_e32 v15, v5
	v_mul_f32_e32 v5, 0xbfb8aa3b, v10
	v_exp_f32_e32 v5, v5
	v_pk_fma_f32 v[16:17], v[22:23], v[54:55], v[76:77]
	v_pk_mul_f32 v[6:7], v[6:7], v[14:15]
	s_waitcnt vmcnt(17)
	v_pk_fma_f32 v[16:17], v[30:31], v[62:63], v[16:17]
	v_add_f32_e32 v5, 1.0, v5
	s_waitcnt vmcnt(16)
; __device__ __forceinline__ unsigned pk2(float lo, float hi) { f32x2_t v = {lo, hi}; bf16x2_t b = __builtin_convertvector(v, bf16x2_t); return __builtin_bit_cast(unsigned, b); }
; __device__ __forceinline__ void fixup_panel(int wave_s, int pm, const float* hbuf, const float* cw, const float* cb, bf16* act) {
;     ...
;         const f32x4 gc0 = wg0 * gm2 + wg1 * gm1 + wg2 * g0 + bg, vc0 = wv0 * vm2 + wv1 * vm1 + wv2 * v0 + bv;
;         const f32x4 gc1 = wg0 * gm1 + wg1 * g0 + wg2 * g1 + bg, vc1 = wv0 * vm1 + wv1 * v0 + wv2 * v1 + bv;
;         f32x4 o0, o1;
; #pragma unroll
;         for (int i = 0; i < 4; ++i) { o0[i] = gc0[i] * __builtin_amdgcn_rcpf(1.0f + __builtin_amdgcn_exp2f(-gc0[i] * LOG2E)) * vc0[i]; o1[i] = gc1[i] * __builtin_amdgcn_rcpf(1.0f + __builtin_amdgcn_exp2f(-gc1[i] * LOG2E)) * vc1[i]; }
;         v2u w0; w0.x = pk2(o0[0], o0[1]); w0.y = pk2(o0[2], o0[3]); v2u w1; w1.x = pk2(o1[0], o1[1]); w1.y = pk2(o1[2], o1[3]);
;         *(v2u*)(act + (size_t)(256 * pm) * DFF + ch) = w0; *(v2u*)(act + (size_t)(256 * pm + 1) * DFF + ch) = w1; }
	v_pk_add_f32 v[16:17], v[66:67], v[16:17]
	v_pk_add_f32 v[8:9], v[52:53], v[8:9]
	v_pk_mul_f32 v[6:7], v[16:17], v[6:7]
	v_rcp_f32_e32 v16, v5
	v_mul_f32_e32 v5, 0xbfb8aa3b, v11
	v_exp_f32_e32 v5, v5
	v_pk_fma_f32 v[12:13], v[12:13], v[40:41], v[44:45]
	v_pk_mul_f32 v[44:45], v[30:31], v[58:59]
	v_pk_fma_f32 v[12:13], v[20:21], v[48:49], v[12:13]
	v_add_f32_e32 v5, 1.0, v5
	v_rcp_f32_e32 v17, v5
	v_mul_f32_e32 v5, 0xbfb8aa3b, v8
	v_exp_f32_e32 v5, v5
	v_pk_fma_f32 v[26:27], v[26:27], v[54:55], v[44:45]
	v_pk_mul_f32 v[10:11], v[10:11], v[16:17]
	v_pk_fma_f32 v[18:19], v[34:35], v[62:63], v[26:27]
	v_add_f32_e32 v5, 1.0, v5
	v_pk_add_f32 v[18:19], v[66:67], v[18:19]
	v_pk_add_f32 v[12:13], v[52:53], v[12:13]
	v_pk_mul_f32 v[10:11], v[18:19], v[10:11]
	v_rcp_f32_e32 v18, v5
	v_mul_f32_e32 v5, 0xbfb8aa3b, v9
	v_exp_f32_e32 v5, v5
	v_pk_mul_f32 v[74:75], v[28:29], v[60:61]
	v_pk_mul_f32 v[42:43], v[32:33], v[60:61]
	v_pk_fma_f32 v[14:15], v[24:25], v[56:57], v[74:75]
	v_add_f32_e32 v5, 1.0, v5
	v_rcp_f32_e32 v19, v5
	v_mul_f32_e32 v5, 0xbfb8aa3b, v12
	v_exp_f32_e32 v5, v5
	v_pk_fma_f32 v[14:15], v[32:33], v[64:65], v[14:15]
	v_pk_mul_f32 v[8:9], v[8:9], v[18:19]
	v_pk_add_f32 v[14:15], v[68:69], v[14:15]
	v_add_f32_e32 v5, 1.0, v5
	v_pk_mul_f32 v[8:9], v[14:15], v[8:9]
	v_rcp_f32_e32 v14, v5
	v_mul_f32_e32 v5, 0xbfb8aa3b, v13
	v_exp_f32_e32 v5, v5
	v_pk_fma_f32 v[28:29], v[28:29], v[56:57], v[42:43]
	v_cvt_pk_bf16_f32 v6, v6, v7
	v_pk_fma_f32 v[16:17], v[36:37], v[64:65], v[28:29]
	v_add_f32_e32 v5, 1.0, v5
	v_rcp_f32_e32 v15, v5
	v_pk_add_f32 v[16:17], v[68:69], v[16:17]
	v_cvt_pk_bf16_f32 v7, v8, v9
	v_cvt_pk_bf16_f32 v8, v10, v11
	v_pk_mul_f32 v[12:13], v[12:13], v[14:15]
	v_lshlrev_b64 v[10:11], 1, v[2:3]
	v_pk_mul_f32 v[12:13], v[16:17], v[12:13]
	v_cvt_pk_bf16_f32 v9, v12, v13
	v_lshl_add_u64 v[12:13], s[40:41], 0, v[10:11]
	global_store_dwordx2 v[12:13], v[6:7], off
	v_lshl_add_u64 v[6:7], s[42:43], 0, v[10:11]
	global_store_dwordx2 v[6:7], v[8:9], off
	s_waitcnt vmcnt(8)
	v_pk_mul_f32 v[196:197], v[134:135], v[166:167]
	s_nop 0
	v_pk_fma_f32 v[130:131], v[130:131], v[162:163], v[196:197]
	v_pk_mul_f32 v[166:167], v[138:139], v[166:167]
	s_waitcnt vmcnt(7)
	v_pk_fma_f32 v[130:131], v[138:139], v[170:171], v[130:131]
	v_pk_fma_f32 v[134:135], v[134:135], v[162:163], v[166:167]
	s_waitcnt vmcnt(6)
	v_pk_add_f32 v[130:131], v[174:175], v[130:131]
	v_pk_fma_f32 v[134:135], v[142:143], v[170:171], v[134:135]
	v_mul_f32_e32 v129, 0xbfb8aa3b, v130
	v_exp_f32_e32 v129, v129
	v_pk_add_f32 v[134:135], v[174:175], v[134:135]
	v_pk_mul_f32 v[194:195], v[136:137], v[168:169]
	s_waitcnt vmcnt(4)
	v_pk_mul_f32 v[200:201], v[150:151], v[182:183]
	v_add_f32_e32 v129, 1.0, v129
	v_rcp_f32_e32 v138, v129
	v_mul_f32_e32 v129, 0xbfb8aa3b, v131
	v_exp_f32_e32 v129, v129
	v_pk_fma_f32 v[132:133], v[132:133], v[164:165], v[194:195]
	v_pk_mul_f32 v[168:169], v[140:141], v[168:169]
	v_pk_fma_f32 v[132:133], v[140:141], v[172:173], v[132:133]
	v_add_f32_e32 v129, 1.0, v129
	v_rcp_f32_e32 v139, v129
	v_mul_f32_e32 v129, 0xbfb8aa3b, v134
	v_exp_f32_e32 v129, v129
	v_pk_fma_f32 v[140:141], v[146:147], v[178:179], v[200:201]
	v_pk_mul_f32 v[130:131], v[130:131], v[138:139]
	s_waitcnt vmcnt(3)
	v_pk_fma_f32 v[140:141], v[154:155], v[186:187], v[140:141]
	v_add_f32_e32 v129, 1.0, v129
	s_waitcnt vmcnt(2)
	v_pk_add_f32 v[140:141], v[190:191], v[140:141]
	v_pk_add_f32 v[132:133], v[176:177], v[132:133]
	v_pk_mul_f32 v[130:131], v[140:141], v[130:131]
	v_rcp_f32_e32 v140, v129
	v_mul_f32_e32 v129, 0xbfb8aa3b, v135
	v_exp_f32_e32 v129, v129
	v_pk_fma_f32 v[136:137], v[136:137], v[164:165], v[168:169]
	v_pk_mul_f32 v[168:169], v[154:155], v[182:183]
	v_pk_fma_f32 v[136:137], v[144:145], v[172:173], v[136:137]
	v_add_f32_e32 v129, 1.0, v129
	v_rcp_f32_e32 v141, v129
	v_mul_f32_e32 v129, 0xbfb8aa3b, v132
	v_exp_f32_e32 v129, v129
	v_pk_fma_f32 v[150:151], v[150:151], v[178:179], v[168:169]
	v_pk_mul_f32 v[134:135], v[134:135], v[140:141]
	v_pk_fma_f32 v[142:143], v[158:159], v[186:187], v[150:151]
	v_add_f32_e32 v129, 1.0, v129
	v_pk_add_f32 v[142:143], v[190:191], v[142:143]
	v_pk_add_f32 v[136:137], v[176:177], v[136:137]
	v_pk_mul_f32 v[134:135], v[142:143], v[134:135]
	v_rcp_f32_e32 v142, v129
	v_mul_f32_e32 v129, 0xbfb8aa3b, v133
	v_exp_f32_e32 v129, v129
	v_pk_mul_f32 v[198:199], v[152:153], v[184:185]
	v_pk_mul_f32 v[166:167], v[156:157], v[184:185]
	v_pk_fma_f32 v[138:139], v[148:149], v[180:181], v[198:199]
	v_add_f32_e32 v129, 1.0, v129
	v_rcp_f32_e32 v143, v129
	v_mul_f32_e32 v129, 0xbfb8aa3b, v136
	v_exp_f32_e32 v129, v129
	v_pk_fma_f32 v[138:139], v[156:157], v[188:189], v[138:139]
	v_pk_mul_f32 v[132:133], v[132:133], v[142:143]
	v_pk_add_f32 v[138:139], v[192:193], v[138:139]
	v_add_f32_e32 v129, 1.0, v129
	v_pk_mul_f32 v[132:133], v[138:139], v[132:133]
	v_rcp_f32_e32 v138, v129
	v_mul_f32_e32 v129, 0xbfb8aa3b, v137
	v_exp_f32_e32 v129, v129
	v_pk_fma_f32 v[152:153], v[152:153], v[180:181], v[166:167]
	v_cvt_pk_bf16_f32 v130, v130, v131
	v_pk_fma_f32 v[140:141], v[160:161], v[188:189], v[152:153]
	v_add_f32_e32 v129, 1.0, v129
	v_rcp_f32_e32 v139, v129
	v_pk_add_f32 v[140:141], v[192:193], v[140:141]
	v_cvt_pk_bf16_f32 v131, v132, v133
	v_cvt_pk_bf16_f32 v132, v134, v135
	v_pk_mul_f32 v[136:137], v[136:137], v[138:139]
	v_lshlrev_b64 v[134:135], 1, v[126:127]
	v_pk_mul_f32 v[136:137], v[140:141], v[136:137]
	v_cvt_pk_bf16_f32 v133, v136, v137
	v_lshl_add_u64 v[136:137], s[40:41], 0, v[134:135]
	global_store_dwordx2 v[136:137], v[130:131], off
	v_lshl_add_u64 v[130:131], s[42:43], 0, v[134:135]
	global_store_dwordx2 v[130:131], v[132:133], off
	s_movk_i32 s2, 0xff80
	v_add_u32_e32 v2, 0x1000, v2
	v_cmp_gt_i32_e32 vcc, s2, v1
	v_add_u32_e32 v4, 0x2000, v4
	s_and_saveexec_b64 s[84:85], vcc
	s_cbranch_execz .Lfx_done
; __device__ __forceinline__ unsigned pk2(float lo, float hi) { f32x2_t v = {lo, hi}; bf16x2_t b = __builtin_convertvector(v, bf16x2_t); return __builtin_bit_cast(unsigned, b); }
; __device__ __forceinline__ void fixup_panel(int wave_s, int pm, const float* hbuf, const float* cw, const float* cb, bf16* act) {
;     ...
;     for (int cgi = tid; cgi < DFF / 4; cgi += NTHR) { const int ch = cgi * 4;
;         const int colg = 256 * (ch >> 7) + (ch & 127);
;         const float* hp = hbuf + ((size_t)(pm - 1) * 4 + 2) * NUP + colg; const float* hc = hbuf + (size_t)pm * 4 * NUP + colg;
;         const f32x4 gm2 = *(const f32x4*)hp, gm1 = *(const f32x4*)(hp + NUP), g0 = *(const f32x4*)hc, g1 = *(const f32x4*)(hc + NUP);
;         const f32x4 vm2 = *(const f32x4*)(hp + 128), vm1 = *(const f32x4*)(hp + NUP + 128), v0 = *(const f32x4*)(hc + 128), v1 = *(const f32x4*)(hc + NUP + 128);
;         const f32x4 wg0 = *(const f32x4*)(cw + ch), wg1 = *(const f32x4*)(cw + NUP + ch), wg2 = *(const f32x4*)(cw + 2 * NUP + ch), bg = *(const f32x4*)(cb + ch);
;         const f32x4 wv0 = *(const f32x4*)(cw + DFF + ch), wv1 = *(const f32x4*)(cw + NUP + DFF + ch), wv2 = *(const f32x4*)(cw + 2 * NUP + DFF + ch), bv = *(const f32x4*)(cb + DFF + ch);
;         const f32x4 gc0 = wg0 * gm2 + wg1 * gm1 + wg2 * g0 + bg, vc0 = wv0 * vm2 + wv1 * vm1 + wv2 * v0 + bv;
;         const f32x4 gc1 = wg0 * gm1 + wg1 * g0 + wg2 * g1 + bg, vc1 = wv0 * vm1 + wv1 * v0 + wv2 * v1 + bv;
;         f32x4 o0, o1;
; #pragma unroll
;         for (int i = 0; i < 4; ++i) { o0[i] = gc0[i] * __builtin_amdgcn_rcpf(1.0f + __builtin_amdgcn_exp2f(-gc0[i] * LOG2E)) * vc0[i]; o1[i] = gc1[i] * __builtin_amdgcn_rcpf(1.0f + __builtin_amdgcn_exp2f(-gc1[i] * LOG2E)) * vc1[i]; }
;         v2u w0; w0.x = pk2(o0[0], o0[1]); w0.y = pk2(o0[2], o0[3]); v2u w1; w1.x = pk2(o1[0], o1[1]); w1.y = pk2(o1[2], o1[3]);
;         *(v2u*)(act + (size_t)(256 * pm) * DFF + ch) = w0; *(v2u*)(act + (size_t)(256 * pm + 1) * DFF + ch) = w1; }
	v_and_b32_e32 v3, 0x7c, v2
	s_movk_i32 s2, 0xff00
	v_and_or_b32 v6, v4, s2, v3
	v_ashrrev_i32_e32 v7, 31, v6
	v_lshlrev_b64 v[6:7], 2, v[6:7]
	v_lshl_add_u64 v[22:23], s[20:21], 0, v[6:7]
	v_add_co_u32_e32 v26, vcc, 0xb000, v22
	v_lshl_add_u64 v[30:31], s[26:27], 0, v[6:7]
	s_nop 0
	v_addc_co_u32_e32 v27, vcc, 0, v23, vcc
	v_ashrrev_i32_e32 v3, 31, v2
	v_add_co_u32_e32 v34, vcc, 0xb000, v30
	v_lshlrev_b64 v[66:67], 2, v[2:3]
	s_nop 0
	v_addc_co_u32_e32 v35, vcc, 0, v31, vcc
	v_lshl_add_u64 v[38:39], s[12:13], 0, v[66:67]
	v_lshl_add_u64 v[42:43], s[28:29], 0, v[66:67]
	global_load_dwordx4 v[6:9], v[22:23], off
	global_load_dwordx4 v[10:13], v[26:27], off
	global_load_dwordx4 v[14:17], v[30:31], off
	global_load_dwordx4 v[18:21], v[34:35], off
	s_nop 0
	global_load_dwordx4 v[22:25], v[22:23], off offset:512
	s_nop 0
	global_load_dwordx4 v[26:29], v[26:27], off offset:512
	s_nop 0
	global_load_dwordx4 v[30:33], v[30:31], off offset:512
	s_nop 0
	global_load_dwordx4 v[34:37], v[34:35], off offset:512
	v_lshl_add_u64 v[46:47], s[30:31], 0, v[66:67]
	global_load_dwordx4 v[38:41], v[38:39], off
	v_lshl_add_u64 v[50:51], s[10:11], 0, v[66:67]
	global_load_dwordx4 v[42:45], v[42:43], off
	v_lshl_add_u64 v[54:55], s[88:89], 0, v[66:67]
	global_load_dwordx4 v[46:49], v[46:47], off
	v_lshl_add_u64 v[58:59], s[90:91], 0, v[66:67]
	global_load_dwordx4 v[50:53], v[50:51], off
	v_lshl_add_u64 v[62:63], s[92:93], 0, v[66:67]
	global_load_dwordx4 v[54:57], v[54:55], off
	v_lshl_add_u64 v[66:67], s[96:97], 0, v[66:67]
	global_load_dwordx4 v[58:61], v[58:59], off
	global_load_dwordx4 v[62:65], v[62:63], off
	global_load_dwordx4 v[66:69], v[66:67], off
	s_waitcnt vmcnt(6)
	v_pk_mul_f32 v[72:73], v[10:11], v[42:43]
	s_nop 0
	v_pk_fma_f32 v[6:7], v[6:7], v[38:39], v[72:73]
	v_pk_mul_f32 v[42:43], v[14:15], v[42:43]
	s_waitcnt vmcnt(5)
	v_pk_fma_f32 v[6:7], v[14:15], v[46:47], v[6:7]
	v_pk_fma_f32 v[10:11], v[10:11], v[38:39], v[42:43]
	s_waitcnt vmcnt(4)
	v_pk_add_f32 v[6:7], v[50:51], v[6:7]
	v_pk_fma_f32 v[10:11], v[18:19], v[46:47], v[10:11]
	v_mul_f32_e32 v5, 0xbfb8aa3b, v6
	v_exp_f32_e32 v5, v5
	v_pk_add_f32 v[10:11], v[50:51], v[10:11]
	v_pk_mul_f32 v[70:71], v[12:13], v[44:45]
	s_waitcnt vmcnt(2)
	v_pk_mul_f32 v[76:77], v[26:27], v[58:59]
	v_add_f32_e32 v5, 1.0, v5
	v_rcp_f32_e32 v14, v5
	v_mul_f32_e32 v5, 0xbfb8aa3b, v7
	v_exp_f32_e32 v5, v5
	v_pk_fma_f32 v[8:9], v[8:9], v[40:41], v[70:71]
	v_pk_mul_f32 v[44:45], v[16:17], v[44:45]
	v_pk_fma_f32 v[8:9], v[16:17], v[48:49], v[8:9]
	v_add_f32_e32 v5, 1.0, v5
	v_rcp_f32_e32 v15, v5
	v_mul_f32_e32 v5, 0xbfb8aa3b, v10
	v_exp_f32_e32 v5, v5
	v_pk_fma_f32 v[16:17], v[22:23], v[54:55], v[76:77]
	v_pk_mul_f32 v[6:7], v[6:7], v[14:15]
	s_waitcnt vmcnt(1)
	v_pk_fma_f32 v[16:17], v[30:31], v[62:63], v[16:17]
	v_add_f32_e32 v5, 1.0, v5
	s_waitcnt vmcnt(0)
	v_pk_add_f32 v[16:17], v[66:67], v[16:17]
	v_pk_add_f32 v[8:9], v[52:53], v[8:9]
	v_pk_mul_f32 v[6:7], v[16:17], v[6:7]
	v_rcp_f32_e32 v16, v5
	v_mul_f32_e32 v5, 0xbfb8aa3b, v11
	v_exp_f32_e32 v5, v5
	v_pk_fma_f32 v[12:13], v[12:13], v[40:41], v[44:45]
	v_pk_mul_f32 v[44:45], v[30:31], v[58:59]
	v_pk_fma_f32 v[12:13], v[20:21], v[48:49], v[12:13]
	v_add_f32_e32 v5, 1.0, v5
	v_rcp_f32_e32 v17, v5
	v_mul_f32_e32 v5, 0xbfb8aa3b, v8
	v_exp_f32_e32 v5, v5
	v_pk_fma_f32 v[26:27], v[26:27], v[54:55], v[44:45]
	v_pk_mul_f32 v[10:11], v[10:11], v[16:17]
	v_pk_fma_f32 v[18:19], v[34:35], v[62:63], v[26:27]
	v_add_f32_e32 v5, 1.0, v5
	v_pk_add_f32 v[18:19], v[66:67], v[18:19]
	v_pk_add_f32 v[12:13], v[52:53], v[12:13]
	v_pk_mul_f32 v[10:11], v[18:19], v[10:11]
	v_rcp_f32_e32 v18, v5
	v_mul_f32_e32 v5, 0xbfb8aa3b, v9
	v_exp_f32_e32 v5, v5
	v_pk_mul_f32 v[74:75], v[28:29], v[60:61]
	v_pk_mul_f32 v[42:43], v[32:33], v[60:61]
	v_pk_fma_f32 v[14:15], v[24:25], v[56:57], v[74:75]
	v_add_f32_e32 v5, 1.0, v5
	v_rcp_f32_e32 v19, v5
	v_mul_f32_e32 v5, 0xbfb8aa3b, v12
	v_exp_f32_e32 v5, v5
	v_pk_fma_f32 v[14:15], v[32:33], v[64:65], v[14:15]
	v_pk_mul_f32 v[8:9], v[8:9], v[18:19]
	v_pk_add_f32 v[14:15], v[68:69], v[14:15]
	v_add_f32_e32 v5, 1.0, v5
	v_pk_mul_f32 v[8:9], v[14:15], v[8:9]
	v_rcp_f32_e32 v14, v5
	v_mul_f32_e32 v5, 0xbfb8aa3b, v13
	v_exp_f32_e32 v5, v5
	v_pk_fma_f32 v[28:29], v[28:29], v[56:57], v[42:43]
	v_cvt_pk_bf16_f32 v6, v6, v7
	v_pk_fma_f32 v[16:17], v[36:37], v[64:65], v[28:29]
	v_add_f32_e32 v5, 1.0, v5
	v_rcp_f32_e32 v15, v5
	v_pk_add_f32 v[16:17], v[68:69], v[16:17]
	v_cvt_pk_bf16_f32 v7, v8, v9
	v_cvt_pk_bf16_f32 v8, v10, v11
	v_pk_mul_f32 v[12:13], v[12:13], v[14:15]
	v_lshlrev_b64 v[10:11], 1, v[2:3]
	v_pk_mul_f32 v[12:13], v[16:17], v[12:13]
	v_cvt_pk_bf16_f32 v9, v12, v13
	v_lshl_add_u64 v[12:13], s[40:41], 0, v[10:11]
	global_store_dwordx2 v[12:13], v[6:7], off
	v_lshl_add_u64 v[6:7], s[42:43], 0, v[10:11]
	global_store_dwordx2 v[6:7], v[8:9], off
.Lfx_done:
	s_or_b64 exec, exec, s[84:85]
